# NA: bias table written to LDS only when the head changes (it is the same for every unit a workgroup processes), which also removes one serialized global round trip from each unit prologue; dead V-frag
# speedup vs baseline: 1.0011x; 1.0011x over previous
; #define LAS __attribute__((address_space(3)))
; template <int KIND> ...
;     ...
;         int base1 = b * 4096, n1 = 64, kr_lo = 0, rs_w = 0, qr = 0, qc = 0, cs = 0;
;         if (KIND == 0) { const int r0 = qb * 4; kr_lo = min(max(r0 - 4, 0), 56); const int kr_hi = min(max(r0 - 1, 0), 56) + 8; base1 += kr_lo * 64; n1 = kr_hi - kr_lo;
;             qr = r0 + (wid >> 1); rs_w = min(max(qr - 4, 0), 56); qc = 32 * (wid & 1) + l32; cs = min(max(qc - 8, 0), 48); }
;         if (isctx) n1 = 0;
;         const int base2 = M_LAT + b * 256, nt = n1 + 4;
;         bf16x8 qf[4];
;         { const bf16_t* qp = qkv + (size_t)(qrow0 + qoff + l32) * N + hq * 64 + 8 * hi;
; #pragma unroll
;           for (int t = 0; t < 4; ++t) qf[t] = *(const bf16x8*)(qp + 16 * t); }
;         if (KIND == 0 && !isctx) { LAS float* bt = (LAS float*)(lds + OFF_BIAS); for (int i = tid; i < 465; i += NTHREADS) bt[i] = rpb[h * 465 + i] * LOG2E; }
;         u32x4 kreg[NK], vreg[NVC];
;         const int krow_l = tid >> 3, kpart = tid & 7;
;     ...
;         float m_ref = 0.f; int first = 1;
;         f32x16 o[NDT], lacc, mneg;
; #pragma unroll
;         for (int dt = 0; dt < NDT; ++dt)
; #pragma unroll
;             for (int j = 0; j < 16; ++j) o[dt][j] = 0.f;
; #pragma unroll
;         for (int j = 0; j < 16; ++j) { lacc[j] = 0.f; mneg[j] = 0.f; }
;         const bf16x8 ones = {(short)0x3F80, (short)0x3F80, (short)0x3F80, (short)0x3F80, (short)0x3F80, (short)0x3F80, (short)0x3F80, (short)0x3F80};
;         ATT_LOAD(0); ATT_STORE(0); __syncthreads();
;         const int koff = kidx * KT + l32 * KSTR + 16 * hi;
;         const int voff = OFF_V + (4 * hi + ((lane & 15) >> 2)) * VSTR + (16 * ((lane >> 4) & 1) + 4 * (lane & 3)) * 2;
;         const int wb = 4 * hi - cs;
;         const int boff0 = OFF_BIAS + 4 * (cs - qc + 15 + wb);
.LBB0_123:
	s_and_b64 s[2:3], s[6:7], exec
	s_movk_i32 s2, 0x880
	s_cselect_b32 s2, s2, 0x800
	v_writelane_b32 v255, s2, 12
	s_cmp_ge_i32 s74, s2
	s_cbranch_scc1 .LBB0_200
	v_writelane_b32 v255, s80, 13
	s_mul_hi_i32 s2, s18, 0x88888889
	s_add_i32 s2, s2, s18
	v_writelane_b32 v255, s81, 14
	v_writelane_b32 v255, s75, 15
	v_writelane_b32 v255, s73, 16
	v_writelane_b32 v255, s78, 17
	s_lshr_b32 s3, s2, 31
	s_ashr_i32 s2, s2, 4
	v_writelane_b32 v255, s79, 18
	v_writelane_b32 v255, s76, 19
	s_add_i32 s2, s2, s3
	s_mul_hi_i32 s3, s2, 0x7440
	v_writelane_b32 v255, s77, 20
	v_writelane_b32 v255, s72, 21
	v_writelane_b32 v255, s65, 22
	v_writelane_b32 v255, s70, 23
	s_mulk_i32 s2, 0x7440
	s_waitcnt lgkmcnt(0)
	s_add_u32 s6, s4, s2
	v_writelane_b32 v255, s71, 24
	v_writelane_b32 v255, s68, 25
	s_addc_u32 s7, s5, s3
	v_and_b32_e32 v197, 31, v196
	v_writelane_b32 v255, s69, 26
	v_writelane_b32 v255, s66, 27
	s_lshl_b32 s2, s38, 5
	v_ashrrev_i32_e32 v4, 31, v198
	v_writelane_b32 v255, s67, 28
	v_writelane_b32 v255, s2, 29
	v_and_or_b32 v0, s2, 32, v197
	s_movk_i32 s2, 0x1d0
	v_lshrrev_b32_e32 v4, 29, v4
	v_cmp_lt_i32_e64 s[2:3], s2, v198
	v_add_u32_e32 v4, v198, v4
	v_ashrrev_i32_e32 v209, 3, v4
	v_writelane_b32 v255, s2, 30
	v_and_b32_e32 v4, -8, v4
	v_sub_u32_e64 v0, v0, 8 clamp
	v_writelane_b32 v255, s3, 31
	v_ashrrev_i32_e32 v208, 3, v198
	v_and_b32_e32 v3, 7, v196
	v_sub_u32_e32 v4, v198, v4
	s_movk_i32 s2, 0xc0
	v_ashrrev_i32_e32 v1, 5, v196
	v_min_u32_e32 v2, 48, v0
	v_lshlrev_b32_e32 v0, 3, v3
	s_waitcnt vmcnt(0)
	v_lshlrev_b32_e32 v154, 3, v4
	v_mul_lo_u32 v5, v208, s90
	v_lshlrev_b32_e32 v192, 4, v3
	v_mul_lo_u32 v3, v209, s2
	v_lshlrev_b32_e32 v4, 4, v4
	v_lshlrev_b32_e32 v152, 3, v1
	v_add3_u32 v210, 0, v5, v192
	v_add3_u32 v211, 0, v3, v4
	v_lshlrev_b32_e32 v4, 4, v1
	v_lshlrev_b32_e32 v1, 2, v1
	v_lshrrev_b32_e32 v5, 2, v196
	v_mul_u32_u24_e32 v3, 0x90, v197
	v_and_or_b32 v5, v5, 3, v1
	v_sub_u32_e32 v1, v1, v2
	v_add3_u32 v212, 0, v3, v4
	v_add_u32_e32 v3, 1, v1
	v_cmp_gt_u32_e64 s[12:13], 16, v3
	v_add_u32_e32 v3, 33, v1
	v_mul_lo_u32 v5, v5, s2
	s_mul_i32 s2, s38, 0x1200
	v_cmp_gt_u32_e64 s[14:15], 16, v3
	v_add_u32_e32 v3, 2, v1
	s_add_i32 s2, s2, 0
	v_cmp_gt_u32_e64 s[18:19], 16, v3
	v_add_u32_e32 v3, 34, v1
	v_and_b32_e32 v6, 16, v196
	v_lshlrev_b32_e32 v7, 2, v196
	v_writelane_b32 v255, s2, 32
	v_and_b32_e32 v2, -16, v1
	s_movk_i32 s2, 0xffe0
	v_cmp_gt_u32_e64 s[22:23], 16, v3
	v_add_u32_e32 v3, 8, v1
	v_and_or_b32 v6, v7, 12, v6
	v_cmp_eq_u32_e64 s[2:3], s2, v2
	v_cmp_gt_u32_e64 s[26:27], 16, v3
	v_add_u32_e32 v3, 40, v1
	v_cmp_eq_u32_e64 s[42:43], s47, v2
	v_add_u32_e32 v2, 17, v1
	v_lshlrev_b32_e32 v6, 1, v6
	v_cmp_gt_u32_e64 s[30:31], 16, v3
	v_add_u32_e32 v3, 10, v1
	v_cmp_gt_u32_e64 s[46:47], 16, v2
	v_add_u32_e32 v2, 49, v1
	v_add3_u32 v213, 0, v5, v6
	v_add_u32_e32 v5, 3, v1
	v_cmp_gt_u32_e64 s[36:37], 16, v3
	v_add_u32_e32 v3, 42, v1
	v_cmp_gt_u32_e64 s[48:49], 16, v2
	v_add_u32_e32 v2, 18, v1
	v_writelane_b32 v255, s2, 33
	v_cmp_gt_u32_e64 s[16:17], 16, v5
	v_add_u32_e32 v5, 35, v1
	v_cmp_gt_u32_e64 s[40:41], 16, v3
	v_add_u32_e32 v3, 19, v1
	v_cmp_gt_u32_e64 s[52:53], 16, v2
	v_add_u32_e32 v2, 50, v1
	v_writelane_b32 v255, s3, 34
	v_cmp_gt_u32_e64 s[2:3], 16, v1
	v_cmp_gt_u32_e64 s[20:21], 16, v5
	v_add_u32_e32 v5, 9, v1
	v_cmp_gt_u32_e64 s[50:51], 16, v3
	v_add_u32_e32 v3, 51, v1
	v_cmp_gt_u32_e64 s[56:57], 16, v2
	v_add_u32_e32 v2, 24, v1
	v_ashrrev_i32_e32 v155, 31, v154
	v_writelane_b32 v255, s2, 35
	v_cmp_gt_u32_e64 s[24:25], 16, v5
	v_add_u32_e32 v5, 41, v1
	v_cmp_gt_u32_e64 s[54:55], 16, v3
	v_add_u32_e32 v3, 25, v1
	v_cmp_gt_u32_e64 s[60:61], 16, v2
	v_add_u32_e32 v2, 56, v1
	s_waitcnt vmcnt(0)
	v_lshl_add_u64 v[156:157], s[58:59], 0, v[192:193]
	v_lshl_add_u64 v[158:159], v[154:155], 1, s[58:59]
	v_writelane_b32 v255, s3, 36
	v_cmp_gt_u32_e64 s[28:29], 16, v5
	v_add_u32_e32 v5, 11, v1
	s_movk_i32 s2, 0xffef
	v_cmp_gt_u32_e64 s[58:59], 16, v3
	v_add_u32_e32 v3, 57, v1
	v_cmp_gt_u32_e64 s[64:65], 16, v2
	v_add_u32_e32 v2, 26, v1
	v_cmp_gt_u32_e64 s[34:35], 16, v5
	v_add_u32_e32 v5, 43, v1
	v_cmp_lt_u32_e64 s[44:45], s2, v1
	v_cmp_gt_u32_e64 s[62:63], 16, v3
	v_add_u32_e32 v3, 27, v1
	v_cmp_gt_u32_e64 s[68:69], 16, v2
	v_add_u32_e32 v2, 58, v1
	v_add_u32_e32 v1, 59, v1
	v_cmp_lt_i32_e32 vcc, v223, v217
	v_cmp_gt_u32_e64 s[70:71], 16, v1
	s_movk_i32 s2, 0x1ff
	v_cndmask_b32_e32 v1, v216, v223, vcc
	v_lshlrev_b32_e32 v214, 2, v1
	v_max_i32_e32 v1, 0xffffffd1, v198
	v_sub_u32_e32 v1, v1, v198
	v_add_u32_e32 v1, 0x1ff, v1
	v_cmp_gt_u32_e64 s[72:73], 16, v2
	v_lshrrev_b32_e32 v2, 9, v1
	s_mov_b32 s3, s38
	v_add_u32_e32 v2, 1, v2
	v_cmp_lt_u32_e64 s[8:9], s2, v1
	v_and_b32_e32 v215, 0xfffffe, v2
	s_lshl_b32 s2, s3, 8
	v_writelane_b32 v255, s8, 37
	s_add_i32 s2, s2, 0
	s_ashr_i32 s4, s38, 1
	v_writelane_b32 v255, s9, 38
	v_cmp_ne_u32_e64 s[8:9], v2, v215
	s_add_i32 s2, s2, 0xa800
	v_lshlrev_b32_e32 v1, 2, v197
	v_writelane_b32 v255, s8, 39
	v_add_u32_e32 v234, s2, v7
	v_sub_u32_e32 v1, v4, v1
	v_writelane_b32 v255, s9, 40
	s_mul_i32 s2, s4, 0x7c
	v_writelane_b32 v255, s4, 41
	v_subrev_u32_e32 v1, s2, v1
	s_and_b32 s2, s3, 1
	v_writelane_b32 v255, s3, 42
	s_lshl_b32 s2, s2, 7
	v_subrev_u32_e32 v1, s2, v1
	v_readlane_b32 s2, v254, 42
	v_writelane_b32 v255, s74, 43
	v_ashrrev_i32_e32 v153, 31, v152
	v_cmp_gt_u32_e64 s[38:39], 16, v5
	v_cmp_gt_u32_e64 s[66:67], 16, v3
	v_lshl_add_u32 v233, v215, 9, v198
	v_add_u32_e32 v199, 0x200, v198
	v_add_u32_e32 v235, s2, v1
	v_lshlrev_b32_e32 v192, 1, v0
	s_mov_b32 s3, s74
	v_writelane_b32 v255, s95, 44
	v_writelane_b32 v255, -1, 50
	s_branch .LBB0_127

; #define LAS __attribute__((address_space(3)))
; template <int KIND> ...
;     ...
;         { const bf16_t* qp = qkv + (size_t)(qrow0 + qoff + l32) * N + hq * 64 + 8 * hi;
; #pragma unroll
;           for (int t = 0; t < 4; ++t) qf[t] = *(const bf16x8*)(qp + 16 * t); }
;         if (KIND == 0 && !isctx) { LAS float* bt = (LAS float*)(lds + OFF_BIAS); for (int i = tid; i < 465; i += NTHREADS) bt[i] = rpb[h * 465 + i] * LOG2E; }
.LBB0_135:
	v_readlane_b32 s8, v255, 29
	s_add_i32 s4, s4, s8
	v_readlane_b32 s8, v255, 5
	v_readlane_b32 s9, v255, 6
	v_add_u32_e32 v2, s4, v197
	s_lshl_b32 s96, s74, 7
	v_mov_b64_e32 v[0:1], s[8:9]
	s_movk_i32 s8, 0x1800
	v_mad_i64_i32 v[0:1], s[76:77], v2, s8, v[0:1]
	v_lshl_add_u64 v[0:1], v[0:1], 0, s[96:97]
	v_lshl_add_u64 v[0:1], v[152:153], 1, v[0:1]
	global_load_dwordx4 v[112:115], v[0:1], off
	global_load_dwordx4 v[116:119], v[0:1], off offset:32
	global_load_dwordx4 v[120:123], v[0:1], off offset:64
	global_load_dwordx4 v[124:127], v[0:1], off offset:96
	v_readlane_b32 s8, v255, 50
	s_nop 0
	s_nop 0
	s_cmp_eq_u32 s74, s8
	s_cbranch_scc1 .LBB0_143
	v_writelane_b32 v255, s74, 50
	v_readlane_b32 s8, v255, 30
	v_readlane_b32 s9, v255, 31
	s_nor_b64 s[76:77], s[8:9], s[78:79]
	s_and_saveexec_b64 s[82:83], s[76:77]
	s_cbranch_execz .LBB0_143
	v_readlane_b32 s8, v255, 37
	s_mov_b64 s[76:77], -1
	v_mov_b32_e32 v0, v198
	v_readlane_b32 s9, v255, 38
	s_and_saveexec_b64 s[90:91], s[8:9]
	s_cbranch_execz .LBB0_140
	s_mul_i32 s75, s74, 0x1d1
	s_mov_b32 s80, s75
	s_mov_b64 s[76:77], 0
	v_mov_b32_e32 v2, v215
	v_mov_b32_e32 v3, v234
	v_mov_b64_e32 v[0:1], v[198:199]

; #define LAS __attribute__((address_space(3)))
; template <int KIND> ...
;     ...
;                 for (int j = 0; j < 16; ++j) s0[j] = __builtin_amdgcn_exp2f(s0[j]);
;                 bf16x8 pf[4];
; #pragma unroll
;                 for (int s = 0; s < 2; ++s) { u32x4 w; w.x = pk2n(s0[8 * s + 0], s0[8 * s + 1]); w.y = pk2n(s0[8 * s + 2], s0[8 * s + 3]); w.z = pk2n(s0[8 * s + 4], s0[8 * s + 5]); w.w = pk2n(s0[8 * s + 6], s0[8 * s + 7]);
;                     pf[s] = __builtin_bit_cast(bf16x8, w); }
;                 __builtin_amdgcn_sched_barrier(0);
; #pragma unroll
;                 for (int s = 0; s < 2; ++s)
; #pragma unroll
;                     for (int dt = 0; dt < NDT; ++dt) {
;                         vfb[s][dt][0] = __builtin_amdgcn_ds_read_tr16_b64_v4i16((LAS s16x4*)(lds + buf * VBUF + voff + (16 * (s + 2)) * VSTR + 64 * dt));
;                         vfb[s][dt][1] = __builtin_amdgcn_ds_read_tr16_b64_v4i16((LAS s16x4*)(lds + buf * VBUF + voff + (16 * (s + 2) + 8) * VSTR + 64 * dt)); }
;                 {
;                     constexpr int NM = 2 * (1 + NDT);
;                     int mi = 0;
; #pragma unroll
;                     for (int s = 0; s < 2; ++s) {
;                         lacc = __builtin_amdgcn_mfma_f32_32x32x16_bf16(ones, pf[s], lacc, 0, 0, 0);
; #pragma unroll
;                         for (int j = (mi * 16) / NM; j < ((mi + 1) * 16) / NM; ++j) s1[j] = __builtin_amdgcn_exp2f(s1[j]);
;                         ++mi;
; #pragma unroll
;                         for (int dt = 0; dt < NDT; ++dt) {
;                             const s16x4 va = vfa[s][dt][0], vb = vfa[s][dt][1];
;                             const bf16x8 vf = {va[0], va[1], va[2], va[3], vb[0], vb[1], vb[2], vb[3]};
;                             o[dt] = __builtin_amdgcn_mfma_f32_32x32x16_bf16(vf, pf[s], o[dt], 0, 0, 0);
; #pragma unroll
;                             for (int j = (mi * 16) / NM; j < ((mi + 1) * 16) / NM; ++j) s1[j] = __builtin_amdgcn_exp2f(s1[j]);
;                             ++mi;
;                         }
;                     }
; #pragma unroll
;                     for (int q = 0; q < 2; ++q) { u32x4 w; w.x = pk2n(s1[8 * q + 0], s1[8 * q + 1]); w.y = pk2n(s1[8 * q + 2], s1[8 * q + 3]); w.z = pk2n(s1[8 * q + 4], s1[8 * q + 5]); w.w = pk2n(s1[8 * q + 6], s1[8 * q + 7]);
;                         pf[q + 2] = __builtin_bit_cast(bf16x8, w); }
; #pragma unroll
.LBB0_161:
	s_cmp_le_i32 s81, s80
	s_cbranch_scc0 nap0_ygen
	v_exp_f32_e32 v64, v80
	v_exp_f32_e32 v79, v81
	v_exp_f32_e32 v81, v82
	v_exp_f32_e32 v82, v83
	v_exp_f32_e32 v83, v84
	v_exp_f32_e32 v84, v85
	v_exp_f32_e32 v85, v86
	v_exp_f32_e32 v86, v87
	v_exp_f32_e32 v87, v88
	v_exp_f32_e32 v88, v89
	v_exp_f32_e32 v89, v90
	v_exp_f32_e32 v90, v91
	v_exp_f32_e32 v91, v92
	v_exp_f32_e32 v92, v93
	v_exp_f32_e32 v93, v94
	v_exp_f32_e32 v94, v95
	v_cvt_pk_bf16_f32 v80, v64, v79
	v_cvt_pk_bf16_f32 v81, v81, v82
	v_cvt_pk_bf16_f32 v82, v83, v84
	v_cvt_pk_bf16_f32 v83, v85, v86
	v_cvt_pk_bf16_f32 v84, v87, v88
	v_cvt_pk_bf16_f32 v85, v89, v90
	v_cvt_pk_bf16_f32 v86, v91, v92
	v_cvt_pk_bf16_f32 v87, v93, v94
	s_waitcnt lgkmcnt(6)
	v_mfma_f32_32x32x16_bf16 v[16:31], v[148:151], v[80:83], v[16:31]
	v_mov_b64_e32 v[90:91], s[86:87]
	v_mov_b64_e32 v[88:89], s[84:85]
	v_exp_f32_e32 v92, v206
	v_exp_f32_e32 v93, v65
	ds_read_b64_tr_b16 v[64:65], v238 offset:24576
	v_mfma_f32_32x32x16_bf16 v[32:47], v[88:91], v[80:83], v[32:47]
	v_exp_f32_e32 v94, v66
	v_exp_f32_e32 v95, v67
	ds_read_b64_tr_b16 v[66:67], v238 offset:26112
	ds_read_b64_tr_b16 v[68:69], v238 offset:24640
	s_waitcnt lgkmcnt(7)
	v_mfma_f32_32x32x16_bf16 v[0:15], v[144:147], v[80:83], v[0:15]
	ds_read_b64_tr_b16 v[70:71], v238 offset:26176
	v_mfma_f32_32x32x16_bf16 v[32:47], v[88:91], v[84:87], v[32:47]
	s_waitcnt lgkmcnt(6)
	v_mfma_f32_32x32x16_bf16 v[16:31], v[140:143], v[84:87], v[16:31]
	v_cvt_pk_bf16_f32 v80, v92, v93
	v_cvt_pk_bf16_f32 v81, v94, v95
	s_waitcnt lgkmcnt(4)
	v_mfma_f32_32x32x16_bf16 v[0:15], v[136:139], v[84:87], v[0:15]
	v_mov_b32_e32 v82, 0
	v_mov_b32_e32 v83, 0
	v_mov_b32_e32 v84, 0
	v_mov_b32_e32 v85, 0
	v_mov_b32_e32 v86, 0
	v_mov_b32_e32 v87, 0
	s_waitcnt lgkmcnt(2)
	v_mfma_f32_32x32x16_bf16 v[16:31], v[64:67], v[80:83], v[16:31]
	s_waitcnt lgkmcnt(0)
	v_mfma_f32_32x32x16_bf16 v[0:15], v[68:71], v[80:83], v[0:15]
	v_mfma_f32_32x32x16_bf16 v[32:47], v[88:91], v[80:83], v[32:47]
	s_waitcnt lgkmcnt(0)
	s_waitcnt lgkmcnt(0)
	s_mov_b32 s82, 0
	s_branch nap0_ydone

; #define LAS __attribute__((address_space(3)))
; template <int KIND> ...
;     ...
;                 s16x4 vfa[2][NDT][2], vfb[2][NDT][2];
; #pragma unroll
;                 for (int s = 0; s < 2; ++s)
; #pragma unroll
;                     for (int dt = 0; dt < NDT; ++dt) {
;                         vfa[s][dt][0] = __builtin_amdgcn_ds_read_tr16_b64_v4i16((LAS s16x4*)(lds + buf * VBUF + voff + (16 * s) * VSTR + 64 * dt));
;                         vfa[s][dt][1] = __builtin_amdgcn_ds_read_tr16_b64_v4i16((LAS s16x4*)(lds + buf * VBUF + voff + (16 * s + 8) * VSTR + 64 * dt)); }
;                 __builtin_amdgcn_sched_barrier(0);
;                 if (na_lat) {
; #pragma unroll
;                     for (int j = 0; j < 16; ++j) { s0[j] += ab0[j]; s1[j] += ab1[j]; }
;                 }
nap1_150:
	s_mulk_i32 s83, 0x3000
	v_add_u32_e32 v238, s83, v213
	s_and_b64 vcc, exec, s[78:79]
	s_cbranch_vccnz nap1_skipR
	ds_read_b64_tr_b16 v[148:149], v238 offset:18432
	ds_read_b64_tr_b16 v[150:151], v238 offset:19968
	ds_read_b64_tr_b16 v[146:147], v238 offset:20032
	ds_read_b64_tr_b16 v[144:145], v238 offset:18496
nap1_skipR:
	ds_read_b64_tr_b16 v[140:141], v238 offset:21504
	ds_read_b64_tr_b16 v[142:143], v238 offset:23040
	ds_read_b64_tr_b16 v[138:139], v238 offset:23104
	ds_read_b64_tr_b16 v[136:137], v238 offset:21568
	s_and_b64 vcc, exec, s[78:79]
	s_cbranch_vccz nap1_152
	v_add_f32_e32 v65, v65, v160
	v_add_f32_e32 v66, v66, v166
	v_add_f32_e32 v67, v67, v167
	v_add_f32_e32 v68, v68, v168
	v_add_f32_e32 v69, v69, v169
	v_add_f32_e32 v70, v70, v172
	v_add_f32_e32 v71, v71, v173
	v_add_f32_e32 v72, v72, v177
	v_add_f32_e32 v73, v73, v178
	v_add_f32_e32 v74, v74, v180
	v_add_f32_e32 v75, v75, v181
	v_add_f32_e32 v76, v76, v186
	v_add_f32_e32 v77, v77, v187
	v_add_f32_e32 v78, v78, v190
	v_add_f32_e32 v206, v64, v236
	v_mov_b32_e32 v80, v229
	v_mov_b32_e32 v81, v229
	v_pk_add_f32 v[94:95], v[110:111], v[200:201]
	v_pk_add_f32 v[92:93], v[108:109], v[188:189]
	v_mov_b32_e32 v90, v229
	v_mov_b32_e32 v91, v229
	v_mov_b32_e32 v88, v229
	v_mov_b32_e32 v89, v229
	v_mov_b32_e32 v86, v229
	v_mov_b32_e32 v87, v229
	v_mov_b32_e32 v84, v229
	v_mov_b32_e32 v85, v229
	v_mov_b32_e32 v82, v229
	v_mov_b32_e32 v83, v229
	v_add_f32_e32 v161, v79, v191
	s_cbranch_execz nap1_153
	s_branch nap1_154

; template <int KIND> ...
;     ...
;         float m_ref = 0.f; int first = 1;
;         f32x16 o[NDT], lacc, mneg;
; #pragma unroll
;         for (int dt = 0; dt < NDT; ++dt)
; #pragma unroll
;             for (int j = 0; j < 16; ++j) o[dt][j] = 0.f;
; #pragma unroll
;         for (int j = 0; j < 16; ++j) { lacc[j] = 0.f; mneg[j] = 0.f; }
;     ...
;             if (t + 1 < nt) ATT_STORE((t + 1) & 1);
;             __syncthreads();
nap1_164:
	s_cmp_eq_u32 s95, s81
	v_add_u32_e32 v237, 0x7c, v237
	s_waitcnt lgkmcnt(0)
	s_barrier
	s_cbranch_scc1 .LBB0_125
	s_mov_b32 s83, s81
	s_branch nap1_145
	s_nop 0
	s_nop 0
	s_nop 0
	s_nop 0
	s_nop 0
	s_nop 0
	s_nop 0
	s_nop 0
	s_nop 0
	s_nop 0
	s_nop 0
	s_nop 0
	s_nop 0
	s_nop 0
	s_nop 0
	s_nop 0
	s_nop 0
	s_nop 0
	s_nop 0
	s_nop 0
	s_nop 0
	s_nop 0
	s_nop 0
	s_nop 0
	s_nop 0
	s_nop 0
	s_nop 0
	s_nop 0
	s_nop 0
	s_nop 0
	s_nop 0
	s_nop 0
	s_nop 0
	s_nop 0
	s_nop 0
	s_nop 0
	s_nop 0
	s_nop 0
	s_nop 0
	s_nop 0
	s_nop 0
	s_nop 0
	s_nop 0
	s_nop 0
	s_nop 0
	s_nop 0
	s_nop 0
	s_nop 0
	s_nop 0
	s_nop 0
	s_nop 0
	s_nop 0
	s_nop 0
	s_nop 0
	s_nop 0
	s_nop 0
	s_nop 0
	s_nop 0
	s_nop 0
	s_nop 0
	s_nop 0
	s_nop 0
	s_nop 0
	s_nop 0
	s_nop 0
	s_nop 0
	s_nop 0
	s_nop 0
	s_nop 0
	s_nop 0
	s_nop 0
	s_nop 0
	s_nop 0
	s_nop 0
	s_nop 0
	s_nop 0
	s_nop 0
	s_nop 0
	s_nop 0
	s_nop 0
	s_nop 0
	s_nop 0
	s_nop 0
	s_nop 0
	s_nop 0
	s_nop 0
	s_nop 0
	s_nop 0
	s_nop 0
	s_nop 0
	s_nop 0
	s_nop 0
	s_nop 0
	s_nop 0
	s_nop 0
	s_nop 0
	s_nop 0
	s_nop 0
	s_nop 0
	s_nop 0
	s_nop 0
	s_nop 0
	s_nop 0
	s_nop 0
	s_nop 0
	s_nop 0
	s_nop 0
	s_nop 0
	s_nop 0
	s_nop 0
	s_nop 0
	s_nop 0
	s_nop 0
	s_nop 0
	s_nop 0
	s_nop 0
	s_nop 0
	s_nop 0
	s_nop 0
	s_nop 0
	s_nop 0
	s_nop 0
	s_nop 0
	s_nop 0
	s_nop 0
	s_nop 0
	s_nop 0
	s_nop 0
	s_nop 0
	s_nop 0
	s_nop 0
	s_nop 0
	s_nop 0
	s_nop 0
	s_nop 0
	s_nop 0
	s_nop 0
	s_nop 0
	s_nop 0
	s_nop 0
	s_nop 0
	s_nop 0
	s_nop 0
	s_nop 0
	s_nop 0
	s_nop 0
	s_nop 0
	s_nop 0
	s_nop 0
	s_nop 0
	s_nop 0
	s_nop 0
	s_nop 0
	s_nop 0
	s_nop 0
	s_nop 0
	s_nop 0
	s_nop 0
	s_nop 0
	s_nop 0
	s_nop 0
	s_nop 0
	s_nop 0
	s_nop 0
	s_nop 0
	s_nop 0
	s_nop 0
	s_nop 0
	s_nop 0
	s_nop 0
	s_nop 0
	s_nop 0
	s_nop 0
	s_nop 0
	s_nop 0
	s_nop 0
	s_nop 0
	s_nop 0
	s_nop 0
	s_nop 0
	s_nop 0
	s_nop 0
	s_nop 0
	s_nop 0
	s_nop 0
	s_nop 0
	s_nop 0
	s_nop 0
	s_nop 0
	s_nop 0
	s_nop 0
	s_nop 0
	s_nop 0
	s_nop 0
	s_nop 0
	s_nop 0
	s_nop 0
	s_nop 0
	s_nop 0
	s_nop 0
	s_nop 0
	s_nop 0
	s_nop 0
	s_nop 0
	s_nop 0
	s_nop 0
	s_nop 0
	s_nop 0
	s_nop 0
	s_nop 0
	s_nop 0
	s_nop 0
	s_nop 0
	s_nop 0
	s_nop 0
	s_nop 0
	s_nop 0
	s_nop 0
	s_nop 0
	s_nop 0
	s_nop 0
	s_nop 0
	s_nop 0
	s_nop 0
	s_nop 0
	s_nop 0
	s_nop 0
	s_nop 0
	s_nop 0
	s_nop 0
	s_nop 0
	s_nop 0
	s_nop 0
	s_nop 0
	s_nop 0
	s_nop 0
	s_nop 0
	s_nop 0
	s_nop 0
	s_nop 0
	s_nop 0
	s_nop 0
	s_nop 0
	s_nop 0
	s_nop 0
	s_nop 0
	s_nop 0
	s_nop 0
	s_nop 0
	s_nop 0
	s_nop 0
	s_nop 0
	s_nop 0
	s_nop 0
	s_nop 0
	s_nop 0
	s_nop 0
	s_nop 0
	s_nop 0
	s_nop 0
	s_nop 0
	s_nop 0
	s_nop 0
	s_nop 0
	s_nop 0
	s_nop 0
	s_nop 0
	s_nop 0
	s_nop 0
	s_nop 0
	s_nop 0
	s_nop 0
	s_nop 0
	s_nop 0
	s_nop 0
	s_nop 0
	s_nop 0
	s_nop 0
	s_nop 0
	s_nop 0
	s_nop 0
	s_nop 0
	s_nop 0
	s_nop 0
	s_nop 0
	s_nop 0
	s_nop 0
	s_nop 0
	s_nop 0
	s_nop 0
	s_nop 0
	s_nop 0
	s_nop 0
	s_nop 0
	s_nop 0
	s_nop 0
	s_nop 0
	s_nop 0
	s_nop 0
	s_nop 0
	s_nop 0
	s_nop 0
	s_nop 0
	s_nop 0
	s_nop 0
	s_nop 0
	s_nop 0
	s_nop 0
	s_nop 0
	s_nop 0
	s_nop 0
	s_nop 0
	s_nop 0
	s_nop 0
	s_nop 0
	s_nop 0
	s_nop 0
	s_nop 0
	s_nop 0
	s_nop 0
	s_nop 0
	s_nop 0
	s_nop 0
	s_nop 0
	s_nop 0
	s_nop 0
	s_nop 0
	s_nop 0
	s_nop 0
	s_nop 0
	s_nop 0
	s_nop 0
	s_nop 0
	s_nop 0
	s_nop 0
	s_nop 0
	s_nop 0
	s_nop 0
	s_nop 0
	s_nop 0
	s_nop 0
	s_nop 0
	s_nop 0
	s_nop 0
	s_nop 0
	s_nop 0
	s_nop 0
	s_nop 0
	s_nop 0
	s_nop 0
	s_nop 0
	s_nop 0
	s_nop 0
	s_nop 0
	s_nop 0
	s_nop 0
	s_nop 0
	s_nop 0
	s_nop 0
	s_nop 0
	s_nop 0
	s_nop 0
	s_nop 0
	s_nop 0
	s_nop 0
	s_nop 0
	s_nop 0
	s_nop 0
	s_nop 0
	s_nop 0
	s_nop 0
	s_nop 0
	s_nop 0
	s_nop 0
	s_nop 0
	s_nop 0
	s_nop 0
	s_nop 0
	s_nop 0
	s_nop 0
	s_nop 0
	s_nop 0
	s_nop 0
	s_nop 0
	s_nop 0
	s_nop 0
	s_nop 0
	s_nop 0
	s_nop 0
	s_nop 0
	s_nop 0
.LBB0_166:
	v_mov_b32_e32 v0, 0
	v_mov_b32_e32 v15, v0
	v_mov_b32_e32 v14, v0
	v_mov_b32_e32 v13, v0
	v_mov_b32_e32 v12, v0
	v_mov_b32_e32 v11, v0
	v_mov_b32_e32 v10, v0
	v_mov_b32_e32 v9, v0
	v_mov_b32_e32 v8, v0
	v_mov_b32_e32 v7, v0
	v_mov_b32_e32 v6, v0
	v_mov_b32_e32 v5, v0
	v_mov_b32_e32 v4, v0
	v_mov_b32_e32 v3, v0
	v_mov_b32_e32 v2, v0
	v_mov_b32_e32 v1, v0
	v_mov_b64_e32 v[46:47], v[14:15]
	v_mov_b32_e32 v31, v0
	v_mov_b32_e32 v30, v0
	v_mov_b32_e32 v29, v0
	v_mov_b32_e32 v28, v0
	v_mov_b32_e32 v27, v0
	v_mov_b32_e32 v26, v0
	v_mov_b32_e32 v25, v0
	v_mov_b32_e32 v24, v0
	v_mov_b32_e32 v23, v0
	v_mov_b32_e32 v22, v0
	v_mov_b32_e32 v21, v0
	v_mov_b32_e32 v20, v0
	v_mov_b32_e32 v19, v0
	v_mov_b32_e32 v18, v0
	v_mov_b32_e32 v17, v0
	v_mov_b32_e32 v16, v0
	v_mov_b64_e32 v[44:45], v[12:13]
	v_mov_b64_e32 v[42:43], v[10:11]
	v_mov_b64_e32 v[40:41], v[8:9]
	v_mov_b64_e32 v[38:39], v[6:7]
	v_mov_b64_e32 v[36:37], v[4:5]
	v_mov_b64_e32 v[34:35], v[2:3]
	v_mov_b64_e32 v[32:33], v[0:1]
	s_branch .LBB0_126
